# v37: v36 + G4 tile loop restructured like G1 (next tile k-tiles prefetched before previous tile epilogue stores; hand-written 16B-store epilogue)
# speedup vs baseline: 1.0466x; 1.0097x over previous
; template <class FL, class FS>
; DI void gemm8_tile(char* shmc, const bf16_t* __restrict__ A, const bf16_t* __restrict__ Bt, const int K, const int brow, const int bcol, FL fl, FS fs) {
;   constexpr int HT = 8192, HALF = 128;
;   bf16_t* shm = (bf16_t*)shmc;
; DI void tile8_order(int L, int nM, int nN, int& pm, int& pn) {
;   const int t = tile_remap(L, nM * nN), nig = 8 * nN, gid = t / nig, fm = gid * 8, gsz = (nM - fm) < 8 ? (nM - fm) : 8;
;   pm = fm + ((t % nig) % gsz); pn = (t % nig) / gsz;
; }
.LBB0_861:
	s_or_b64 exec, exec, s[6:7]
	s_mov_b32 s0, 0
	s_waitcnt lgkmcnt(0)
	s_barrier
	s_ashr_i32 s1, s0, 31
	v_readlane_b32 s2, v251, 3
	v_readlane_b32 s3, v251, 4
	s_add_u32 s0, s2, s0
	s_addc_u32 s1, s3, s1
	s_load_dwordx4 s[20:23], s[0:1], 0xf0
	v_readlane_b32 s73, v251, 0
	v_mov_b32_e32 v0, v182
	s_waitcnt lgkmcnt(0)
	s_add_u32 s24, s22, 0x1110000
	s_addc_u32 s25, s23, 0
	s_cmpk_lt_i32 s73, 0xc00
	s_cbranch_scc0 .LBB0_1175
	s_add_u32 s33, s22, 0x1800000
	s_addc_u32 s60, s23, 0
	s_add_u32 s61, s22, 0x800000
	s_addc_u32 s62, s23, 0
	s_add_u32 s26, s22, 0x11900000
	s_addc_u32 s27, s23, 0
	s_add_u32 s28, s22, 0x9880000
	s_addc_u32 s29, s23, 0
	s_add_u32 s30, s20, 0x10df0000
	s_addc_u32 s31, s21, 0
	s_add_u32 s20, s20, 0x10540000
	s_addc_u32 s21, s21, 0
	s_mov_b32 s63, 0x10000
	s_mov_b32 s64, 0x14000
	s_mov_b64 s[34:35], 0x80
	s_mov_b32 s65, 0x18000
	s_mov_b32 s66, 0x1c000
	s_mov_b64 s[36:37], 0x1840080
	s_mov_b64 s[38:39], 0x800100
	s_mov_b64 s[40:41], 0x1800100
	s_mov_b64 s[42:43], 0x840100
	s_mov_b64 s[44:45], 0x1840100
	s_mov_b64 s[46:47], 0x800180
	s_mov_b64 s[48:49], 0x1800180
	s_mov_b64 s[50:51], 0x840180
	s_mov_b64 s[52:53], 0x100
	s_mov_b64 s[54:55], 0x780
	s_movk_i32 s67, 0x100
	v_mov_b32_e32 v129, 0
	s_movk_i32 s68, 0x7ff
	s_movk_i32 s69, 0xc10
	s_mov_b32 s70, 0xffff
	s_movk_i32 s71, 0x1fff
	s_movk_i32 s72, 0x1ffc
	v_mov_b32_e32 v142, 1
	s_mov_b32 s98, 0
	s_branch .LBB0_866
.LBB0_866:
	s_lshl_b32 s0, s73, 5
	s_and_b32 s0, s0, 0xe0
	s_mul_i32 s0, s0, 12
	s_ashr_i32 s1, s73, 3
	s_add_i32 s0, s0, s1
	v_mov_b32_e32 v128, v182
	s_mul_hi_i32 s1, s0, 0x2aaaaaab
	s_lshr_b32 s2, s1, 31
	v_ashrrev_i32_e32 v200, 31, v128
	s_ashr_i32 s1, s1, 4
	v_lshrrev_b32_e32 v200, 26, v200
	s_add_i32 s1, s1, s2
	v_add_u32_e32 v200, v128, v200
	s_mul_i32 s2, s1, 0x60
	v_ashrrev_i32_e32 v201, 6, v200
	v_bfe_i32 v200, v128, 27, 1
	s_sub_i32 s0, s0, s2
	v_lshlrev_b32_e32 v147, 4, v128
	v_lshrrev_b32_e32 v200, 22, v200
	s_bfe_i32 s2, s0, 0x80000
	v_add_u32_e32 v200, v147, v200
	s_bfe_u32 s2, s2, 0x3000c
	v_and_b32_e32 v200, 0xfffffc00, v200
	s_add_i32 s2, s0, s2
	v_sub_u32_e32 v200, v147, v200
	s_bfe_i32 s3, s2, 0x80000
	s_and_b32 s2, s2, 0xf8
	v_lshrrev_b32_e32 v202, 4, v200
	s_sub_i32 s0, s0, s2
	v_bitop3_b32 v202, v202, v200, 32 bitop3:0x6c
	v_ashrrev_i32_e32 v200, 31, v200
	s_sext_i32_i8 s0, s0
	v_lshrrev_b32_e32 v200, 26, v200
	s_sext_i32_i16 s3, s3
	s_lshl_b32 s1, s1, 11
	s_lshl_b32 s0, s0, 8
	v_lshlrev_b32_e32 v203, 3, v201
	v_add_u32_e32 v200, v202, v200
	s_add_i32 s6, s0, s1
	s_lshl_b32 s0, s3, 5
	v_and_b32_e32 v203, -16, v203
	v_ashrrev_i32_e32 v204, 6, v200
	s_and_b32 s56, s0, 0xffffff00
	v_add_u32_e32 v200, v204, v203
	v_mul_i32_i24_e32 v203, 64, v204
	s_ashr_i32 s57, s56, 31
	v_lshlrev_b32_e32 v201, 5, v201
	v_sub_u32_e32 v202, v202, v203
	s_lshl_b64 s[0:1], s[56:57], 11
	v_and_b32_e32 v201, 32, v201
	v_ashrrev_i16_sdwa v202, v142, sext(v202) dst_sel:DWORD dst_unused:UNUSED_PAD src0_sel:DWORD src1_sel:BYTE_0
	s_add_u32 s2, s61, s0
	v_add_u32_sdwa v202, v201, sext(v202) dst_sel:DWORD dst_unused:UNUSED_PAD src0_sel:DWORD src1_sel:WORD_0
	v_ashrrev_i32_e32 v201, 31, v200
	s_addc_u32 s3, s62, s1
	v_lshlrev_b64 v[200:201], 11, v[200:201]
	v_ashrrev_i32_e32 v203, 31, v202
	v_lshl_add_u64 v[204:205], s[2:3], 0, v[200:201]
	v_lshlrev_b64 v[202:203], 1, v[202:203]
	v_add_u32_e32 v153, 0x2000, v147
	v_lshl_add_u64 v[208:209], v[204:205], 0, v[202:203]
	v_ashrrev_i32_e32 v204, 31, v153
	v_lshrrev_b32_e32 v204, 22, v204
	v_add_u32_e32 v204, v153, v204
	v_ashrrev_i32_e32 v205, 10, v204
	v_mul_i32_i24_e32 v204, 0x400, v205
	v_sub_u32_e32 v204, v153, v204
	v_lshrrev_b32_e32 v206, 4, v204
	v_bitop3_b32 v206, v206, v204, 32 bitop3:0x6c
	v_ashrrev_i32_e32 v207, 31, v206
	v_lshrrev_b32_e32 v207, 26, v207
	v_add_u32_e32 v207, v206, v207
	v_lshlrev_b32_e32 v204, 3, v205
	v_ashrrev_i32_e32 v210, 6, v207
	v_and_b32_e32 v207, 0xc0, v207
	v_and_b32_e32 v204, -16, v204
	v_lshlrev_b32_e32 v205, 5, v205
	v_sub_u32_e32 v206, v206, v207
	v_add_u32_e32 v204, v210, v204
	v_and_b32_e32 v205, 32, v205
	v_ashrrev_i16_sdwa v206, v142, sext(v206) dst_sel:DWORD dst_unused:UNUSED_PAD src0_sel:DWORD src1_sel:BYTE_0
	v_add_u32_e32 v149, 0x10000, v147
	v_add_u32_sdwa v206, v205, sext(v206) dst_sel:DWORD dst_unused:UNUSED_PAD src0_sel:DWORD src1_sel:WORD_0
	v_ashrrev_i32_e32 v205, 31, v204
	v_readfirstlane_b32 s4, v149
	v_lshlrev_b64 v[204:205], 11, v[204:205]
	v_add_u32_e32 v155, 0x12000, v147
	s_mov_b32 m0, s4
	v_lshl_add_u64 v[210:211], s[2:3], 0, v[204:205]
	v_readfirstlane_b32 s2, v155
	s_ashr_i32 s7, s6, 31
	global_load_lds_dwordx4 v[208:209], off
	s_mov_b32 m0, s2
	s_lshl_b64 s[2:3], s[6:7], 11
	v_ashrrev_i32_e32 v207, 31, v206
	s_add_u32 s4, s33, s2
	v_lshlrev_b64 v[206:207], 1, v[206:207]
	s_addc_u32 s5, s60, s3
; DI int otid() { int t = threadIdx.x; asm volatile("" : "+v"(t)); return t; }
; #define STAGE(P, BASE, br, kt) do { const long _g = (long)(br) * K + (long)(kt) * 64; \
;     _Pragma("unroll") for (int _i = 0; _i < 2; ++_i) { const int _b = tidx * 16 + _i * 8192; int _r, _c; stage_rc8(_b, _r, _c); \
;       __builtin_amdgcn_global_load_lds((const unsigned*)(BASE + _g + (long)_r * K + _c), (LAS unsigned*)((LAS char*)(P) + _b), 16, 0, 0); } } while (0)
; #define WAIT_V(n) asm volatile("s_waitcnt vmcnt(" #n ")" ::: "memory")
; #define BAR __builtin_amdgcn_s_barrier()
; template <class FL, class FS>
; DI void gemm8_tile(char* shmc, const bf16_t* __restrict__ A, const bf16_t* __restrict__ Bt, const int K, const int brow, const int bcol, FL fl, FS fs) {
;     ...
;   const int tidx = otid();
;   const int wid = tidx >> 6, lane = tidx & 63, wr = wid >> 2, wc = wid & 3, fr = lane & 15, fq = lane >> 4;
;   f32x4 acc[2][2][4][2];
; #pragma unroll
;   for (int a = 0; a < 2; ++a)
; #pragma unroll
;     for (int b = 0; b < 2; ++b)
; #pragma unroll
;       for (int m = 0; m < 4; ++m)
; #pragma unroll
;         for (int n = 0; n < 2; ++n) acc[a][b][m][n] = (f32x4){0.f, 0.f, 0.f, 0.f};
;   bf16x8 At[4][2], B0[2][2], B1[2][2];
;   const int nt = K / 64;
;   STAGE(SB(0, 0), Bt, bcol, 0); STAGE(SA(0, 0), A, brow, 0);
;   STAGE(SB(0, 1), Bt, bcol + HALF, 0); STAGE(SA(0, 1), A, brow + HALF, 0);
;   if (wr == 1) BAR;
;   WAIT_V(4); BAR;
;   STAGE(SB(1, 0), Bt, bcol, 1); STAGE(SA(1, 0), A, brow, 1); STAGE(SB(1, 1), Bt, bcol + HALF, 1);
;   WAIT_V(6); BAR;
	v_lshl_add_u64 v[210:211], v[210:211], 0, v[206:207]
	v_lshl_add_u64 v[212:213], s[4:5], 0, v[200:201]
	v_readfirstlane_b32 s7, v147
	global_load_lds_dwordx4 v[210:211], off
	v_lshl_add_u64 v[212:213], v[212:213], 0, v[202:203]
	s_mov_b32 m0, s7
	v_lshl_add_u64 v[214:215], s[4:5], 0, v[204:205]
	v_readfirstlane_b32 s4, v153
	global_load_lds_dwordx4 v[212:213], off
	s_mov_b32 m0, s4
	s_or_b32 s4, s56, 0x80
	s_ashr_i32 s5, s4, 31
	s_lshl_b64 s[4:5], s[4:5], 11
	s_add_u32 s4, s61, s4
	s_addc_u32 s5, s62, s5
	v_add_u32_e32 v157, 0x14000, v147
	v_lshl_add_u64 v[214:215], v[214:215], 0, v[206:207]
	v_lshl_add_u64 v[216:217], s[4:5], 0, v[200:201]
	v_readfirstlane_b32 s7, v157
	v_add_u32_e32 v158, 0x16000, v147
	global_load_lds_dwordx4 v[214:215], off
	v_lshl_add_u64 v[216:217], v[216:217], 0, v[202:203]
	s_mov_b32 m0, s7
	v_lshl_add_u64 v[218:219], s[4:5], 0, v[204:205]
	v_readfirstlane_b32 s4, v158
	global_load_lds_dwordx4 v[216:217], off
	s_mov_b32 m0, s4
	s_or_b32 s4, s6, 0x80
	s_ashr_i32 s5, s4, 31
	s_lshl_b64 s[4:5], s[4:5], 11
	s_add_u32 s4, s33, s4
	s_addc_u32 s5, s60, s5
	v_add_u32_e32 v159, 0x4000, v147
	v_lshl_add_u64 v[218:219], v[218:219], 0, v[206:207]
	v_lshl_add_u64 v[220:221], s[4:5], 0, v[200:201]
	v_readfirstlane_b32 s7, v159
	v_add_u32_e32 v160, 0x6000, v147
	global_load_lds_dwordx4 v[218:219], off
	v_lshl_add_u64 v[130:131], v[220:221], 0, v[202:203]
	s_mov_b32 m0, s7
	v_lshl_add_u64 v[220:221], s[4:5], 0, v[204:205]
	v_readfirstlane_b32 s4, v160
	global_load_lds_dwordx4 v[130:131], off
	v_lshl_add_u64 v[132:133], v[220:221], 0, v[206:207]
	s_mov_b32 m0, s4
	v_ashrrev_i32_e32 v220, 8, v128
	global_load_lds_dwordx4 v[132:133], off
	v_add_u32_e32 v161, 0x18000, v147
	v_add_u32_e32 v162, 0x1a000, v147
	v_readfirstlane_b32 s4, v161
	v_lshl_add_u64 v[208:209], v[208:209], 0, s[34:35]
	s_mov_b32 m0, s4
	v_readfirstlane_b32 s4, v162
	v_add_u32_e32 v163, 0x8000, v147
	global_load_lds_dwordx4 v[208:209], off
	v_lshl_add_u64 v[208:209], v[210:211], 0, s[34:35]
	s_mov_b32 m0, s4
	v_readfirstlane_b32 s4, v163
	v_add_u32_e32 v164, 0xa000, v147
	global_load_lds_dwordx4 v[208:209], off
	v_lshl_add_u64 v[208:209], v[212:213], 0, s[34:35]
	s_mov_b32 m0, s4
	v_readfirstlane_b32 s4, v164
	v_add_u32_e32 v165, 0x1c000, v147
	global_load_lds_dwordx4 v[208:209], off
	v_lshl_add_u64 v[208:209], v[214:215], 0, s[34:35]
	s_mov_b32 m0, s4
	v_readfirstlane_b32 s4, v165
	v_add_u32_e32 v167, 0x1e000, v147
	global_load_lds_dwordx4 v[208:209], off
	v_lshl_add_u64 v[208:209], v[216:217], 0, s[34:35]
	s_mov_b32 m0, s4
	v_readfirstlane_b32 s4, v167
	global_load_lds_dwordx4 v[208:209], off
	v_lshl_add_u64 v[208:209], v[218:219], 0, s[34:35]
	s_mov_b32 m0, s4
	v_and_b32_e32 v143, 15, v128
	global_load_lds_dwordx4 v[208:209], off
	v_bfe_u32 v145, v128, 4, 2
	v_lshlrev_b32_e32 v212, 2, v128
	v_lshlrev_b32_e32 v208, 4, v145
	v_lshlrev_b32_e32 v209, 6, v143
	v_and_b32_e32 v212, 32, v212
	v_or_b32_e32 v211, v208, v209
	v_bitop3_b32 v213, v208, v212, v209 bitop3:0x36
	v_lshlrev_b32_e32 v209, 6, v128
	v_and_b32_e32 v209, 0x3c0, v209
	v_bitop3_b32 v214, v211, s63, v212 bitop3:0xde
	v_bitop3_b32 v215, v211, s64, v212 bitop3:0xde
	v_bitop3_b32 v216, v211, s65, v212 bitop3:0xde
	v_bitop3_b32 v211, v211, s66, v212 bitop3:0xde
	v_bitop3_b32 v212, v209, v212, v208 bitop3:0x36
	v_lshl_add_u64 v[208:209], s[0:1], 0, v[200:201]
	v_lshl_add_u64 v[200:201], s[2:3], 0, v[200:201]
	v_bfe_u32 v144, v128, 6, 2
	v_lshlrev_b32_e32 v217, 13, v220
	v_lshl_add_u64 v[138:139], v[200:201], 0, v[202:203]
	v_lshl_add_u64 v[200:201], s[2:3], 0, v[204:205]
	v_lshlrev_b32_e32 v210, 12, v144
	v_lshlrev_b32_e32 v146, 6, v220
	v_or_b32_e32 v218, 0x800, v217
	v_or_b32_e32 v219, 0x1000, v217
	v_or_b32_e32 v220, 0x1800, v217
	v_lshl_add_u64 v[134:135], v[208:209], 0, v[202:203]
	v_lshl_add_u64 v[208:209], s[0:1], 0, v[204:205]
	v_lshl_add_u64 v[140:141], v[200:201], 0, v[206:207]
	v_lshl_add_u64 v[136:137], v[208:209], 0, v[206:207]
	v_add_u32_e32 v170, v214, v210
	v_add_u32_e32 v152, v213, v217
	v_add_u32_e32 v151, v212, v218
	v_add_u32_e32 v150, v212, v219
	v_add_u32_e32 v148, v212, v220
	v_add_u32_e32 v169, 0xc000, v147
	v_add_u32_e32 v168, 0xe000, v147
	v_add_u32_e32 v166, v215, v210
	v_add_u32_e32 v156, v216, v210
	v_add_u32_e32 v154, v211, v210
	v_lshl_add_u64 v[222:223], s[22:23], 0, v[138:139]
	v_readfirstlane_b32 s1, v169
	v_lshl_add_u64 v[222:223], v[222:223], 0, s[36:37]
	s_mov_b32 m0, s1
	v_lshl_add_u64 v[224:225], s[22:23], 0, v[140:141]
	v_readfirstlane_b32 s1, v168
	global_load_lds_dwordx4 v[222:223], off
	v_lshl_add_u64 v[224:225], v[224:225], 0, s[36:37]
	s_mov_b32 m0, s1
	s_nop 0
	global_load_lds_dwordx4 v[224:225], off
	s_cmp_eq_u32 s98, 0
	s_cbranch_scc1 .Lg4_first
	s_mov_b32 s101, 0
	s_branch .Lg4_epi

; #define STAGE(P, BASE, br, kt) do { const long _g = (long)(br) * K + (long)(kt) * 64; \
;     _Pragma("unroll") for (int _i = 0; _i < 2; ++_i) { const int _b = tidx * 16 + _i * 8192; int _r, _c; stage_rc8(_b, _r, _c); \
;       __builtin_amdgcn_global_load_lds((const unsigned*)(BASE + _g + (long)_r * K + _c), (LAS unsigned*)((LAS char*)(P) + _b), 16, 0, 0); } } while (0)
; #define LDA(dst, b, h) _Pragma("unroll") for (int m = 0; m < 4; ++m) _Pragma("unroll") for (int k = 0; k < 2; ++k) \
;     dst[m][k] = *reinterpret_cast<const bf16x8*>((const char*)SA(b, h) + lds_byte8(wr * 64 + m * 16 + fr, k * 32 + fq * 8))
; #define LDB(dst, b, h) _Pragma("unroll") for (int n = 0; n < 2; ++n) _Pragma("unroll") for (int k = 0; k < 2; ++k) \
;     dst[n][k] = *reinterpret_cast<const bf16x8*>((const char*)SB(b, h) + lds_byte8(wc * 32 + n * 16 + fr, k * 32 + fq * 8))
; #define MMA(ai, bj, At_, Bt_) do { __builtin_amdgcn_s_setprio(1); \
;     _Pragma("unroll") for (int m = 0; m < 4; ++m) _Pragma("unroll") for (int n = 0; n < 2; ++n) _Pragma("unroll") for (int k = 0; k < 2; ++k) \
;       acc[ai][bj][m][n] = MFMA16(Bt_[n][k], At_[m][k], acc[ai][bj][m][n]); \
;     __builtin_amdgcn_s_setprio(0); } while (0)
; #define WAIT_V(n) asm volatile("s_waitcnt vmcnt(" #n ")" ::: "memory")
; #define WAIT_L(n) asm volatile("s_waitcnt lgkmcnt(" #n ")" ::: "memory")
; #define BAR __builtin_amdgcn_s_barrier()
; #define SCHED __builtin_amdgcn_sched_barrier(0)
; template <class FL, class FS>
; DI void gemm8_tile(char* shmc, const bf16_t* __restrict__ A, const bf16_t* __restrict__ Bt, const int K, const int brow, const int bcol, FL fl, FS fs) {
;     ...
;   for (int t = 0; t < nt - 2; t += 2) {
;     LDB(B0, 0, 0); SCHED; LDA(At, 0, 0); STAGE(SA(1, 1), A, brow + HALF, t + 1);
;     WAIT_L(8); BAR; WAIT_L(0); MMA(0, 0, At, B0); BAR; SCHED;
;     LDB(B1, 0, 1); STAGE(SB(0, 0), Bt, bcol, t + 2);
;     BAR; WAIT_L(0); MMA(0, 1, At, B1); BAR;
;     LDA(At, 0, 1); STAGE(SA(0, 0), A, brow, t + 2);
;     BAR; WAIT_L(0); MMA(1, 0, At, B0); BAR; SCHED;
;     STAGE(SB(0, 1), Bt, bcol + HALF, t + 2);
;     WAIT_V(6); BAR; MMA(1, 1, At, B1); BAR;
;     LDB(B0, 1, 0); SCHED; LDA(At, 1, 0); STAGE(SA(0, 1), A, brow + HALF, t + 2);
;     WAIT_L(8); BAR; WAIT_L(0); MMA(0, 0, At, B0); BAR; SCHED;
.LBB0_869:
	ds_read_b128 v[172:175], v170
	ds_read_b128 v[176:179], v170 offset:1024
	ds_read_b128 v[184:187], v170 offset:2048
	ds_read_b128 v[188:191], v170 offset:3072
	v_lshl_add_u64 v[180:181], s[22:23], 0, v[138:139]
	v_readfirstlane_b32 s1, v169
	v_lshl_add_u64 v[224:225], v[180:181], 0, s[36:37]
	s_mov_b32 m0, s1
	v_lshl_add_u64 v[240:241], s[22:23], 0, v[140:141]
	v_readfirstlane_b32 s1, v168
	ds_read_b128 v[192:195], v152
	ds_read_b128 v[196:199], v152 offset:1024
	ds_read_b128 v[200:203], v151
	ds_read_b128 v[204:207], v151 offset:1024
	ds_read_b128 v[208:211], v150
	ds_read_b128 v[212:215], v150 offset:1024
	ds_read_b128 v[216:219], v148
	ds_read_b128 v[220:223], v148 offset:1024
	s_cmp_eq_u32 s0, -2
	s_cbranch_scc1 .Lg4_p1skip
	global_load_lds_dwordx4 v[224:225], off
	v_lshl_add_u64 v[224:225], v[240:241], 0, s[36:37]
	s_mov_b32 m0, s1
	s_nop 0
	global_load_lds_dwordx4 v[224:225], off
.Lg4_p1skip:
	s_waitcnt lgkmcnt(8)
	s_barrier
	s_waitcnt lgkmcnt(0)
	s_setprio 1
	s_waitcnt lgkmcnt(0)
	v_mfma_f32_16x16x32_bf16 v[124:127], v[172:175], v[192:195], v[124:127]
	v_mfma_f32_16x16x32_bf16 v[120:123], v[184:187], v[192:195], v[120:123]
	v_mfma_f32_16x16x32_bf16 v[116:119], v[172:175], v[200:203], v[116:119]
	v_mfma_f32_16x16x32_bf16 v[112:115], v[184:187], v[200:203], v[112:115]
	v_mfma_f32_16x16x32_bf16 v[108:111], v[172:175], v[208:211], v[108:111]
	v_mfma_f32_16x16x32_bf16 v[104:107], v[184:187], v[208:211], v[104:107]
	v_mfma_f32_16x16x32_bf16 v[100:103], v[172:175], v[216:219], v[100:103]
	v_mfma_f32_16x16x32_bf16 v[96:99], v[184:187], v[216:219], v[96:99]
	v_mfma_f32_16x16x32_bf16 v[124:127], v[176:179], v[196:199], v[124:127]
	v_mfma_f32_16x16x32_bf16 v[120:123], v[188:191], v[196:199], v[120:123]
	v_mfma_f32_16x16x32_bf16 v[116:119], v[176:179], v[204:207], v[116:119]
	v_mfma_f32_16x16x32_bf16 v[112:115], v[188:191], v[204:207], v[112:115]
	v_mfma_f32_16x16x32_bf16 v[108:111], v[176:179], v[212:215], v[108:111]
	v_mfma_f32_16x16x32_bf16 v[104:107], v[188:191], v[212:215], v[104:107]
	v_mfma_f32_16x16x32_bf16 v[100:103], v[176:179], v[220:223], v[100:103]
	v_mfma_f32_16x16x32_bf16 v[96:99], v[188:191], v[220:223], v[96:99]
	s_setprio 0
	s_barrier
	v_lshl_add_u64 v[242:243], s[22:23], 0, v[134:135]
	v_readfirstlane_b32 s1, v149
	v_lshl_add_u64 v[244:245], v[242:243], 0, s[38:39]
	s_mov_b32 m0, s1
	ds_read_b128 v[224:227], v166
	ds_read_b128 v[228:231], v166 offset:1024
	ds_read_b128 v[232:235], v166 offset:2048
	ds_read_b128 v[236:239], v166 offset:3072
	global_load_lds_dwordx4 v[244:245], off
	v_lshl_add_u64 v[244:245], s[22:23], 0, v[136:137]
	v_readfirstlane_b32 s1, v155
	v_lshl_add_u64 v[246:247], v[244:245], 0, s[38:39]
	s_mov_b32 m0, s1
	s_nop 0
	global_load_lds_dwordx4 v[246:247], off
	s_barrier
	s_waitcnt lgkmcnt(0)
	s_setprio 1
	s_waitcnt lgkmcnt(0)
	v_mfma_f32_16x16x32_bf16 v[92:95], v[224:227], v[192:195], v[92:95]
	v_mfma_f32_16x16x32_bf16 v[88:91], v[232:235], v[192:195], v[88:91]
	v_mfma_f32_16x16x32_bf16 v[84:87], v[224:227], v[200:203], v[84:87]
	v_mfma_f32_16x16x32_bf16 v[80:83], v[232:235], v[200:203], v[80:83]
	v_mfma_f32_16x16x32_bf16 v[76:79], v[224:227], v[208:211], v[76:79]
	v_mfma_f32_16x16x32_bf16 v[72:75], v[232:235], v[208:211], v[72:75]
	v_mfma_f32_16x16x32_bf16 v[68:71], v[224:227], v[216:219], v[68:71]
	v_mfma_f32_16x16x32_bf16 v[64:67], v[232:235], v[216:219], v[64:67]
	v_mfma_f32_16x16x32_bf16 v[92:95], v[228:231], v[196:199], v[92:95]
	v_mfma_f32_16x16x32_bf16 v[88:91], v[236:239], v[196:199], v[88:91]
	v_mfma_f32_16x16x32_bf16 v[84:87], v[228:231], v[204:207], v[84:87]
	v_mfma_f32_16x16x32_bf16 v[80:83], v[236:239], v[204:207], v[80:83]
	v_mfma_f32_16x16x32_bf16 v[76:79], v[228:231], v[212:215], v[76:79]
	v_mfma_f32_16x16x32_bf16 v[72:75], v[236:239], v[212:215], v[72:75]
	v_mfma_f32_16x16x32_bf16 v[68:71], v[228:231], v[220:223], v[68:71]
	v_mfma_f32_16x16x32_bf16 v[64:67], v[236:239], v[220:223], v[64:67]
	s_setprio 0
	v_readfirstlane_b32 s1, v147
	v_lshl_add_u64 v[246:247], v[180:181], 0, s[40:41]
	s_mov_b32 m0, s1
	v_readfirstlane_b32 s1, v153
	s_barrier
	ds_read_b128 v[192:195], v152 offset:16384
	ds_read_b128 v[196:199], v152 offset:17408
	ds_read_b128 v[200:203], v151 offset:16384
	ds_read_b128 v[204:207], v151 offset:17408
	ds_read_b128 v[208:211], v150 offset:16384
	ds_read_b128 v[212:215], v150 offset:17408
	ds_read_b128 v[216:219], v148 offset:16384
	ds_read_b128 v[220:223], v148 offset:17408
	global_load_lds_dwordx4 v[246:247], off
	v_lshl_add_u64 v[246:247], v[240:241], 0, s[40:41]
	s_mov_b32 m0, s1
	s_nop 0
	global_load_lds_dwordx4 v[246:247], off
	s_barrier
	s_waitcnt lgkmcnt(0)
	s_setprio 1
	s_waitcnt lgkmcnt(0)
	v_mfma_f32_16x16x32_bf16 v[60:63], v[172:175], v[192:195], v[60:63]
	v_mfma_f32_16x16x32_bf16 v[56:59], v[184:187], v[192:195], v[56:59]
	v_mfma_f32_16x16x32_bf16 v[52:55], v[172:175], v[200:203], v[52:55]
	v_mfma_f32_16x16x32_bf16 v[48:51], v[184:187], v[200:203], v[48:51]
	v_mfma_f32_16x16x32_bf16 v[44:47], v[172:175], v[208:211], v[44:47]
	v_mfma_f32_16x16x32_bf16 v[40:43], v[184:187], v[208:211], v[40:43]
	v_mfma_f32_16x16x32_bf16 v[36:39], v[172:175], v[216:219], v[36:39]
	v_mfma_f32_16x16x32_bf16 v[32:35], v[184:187], v[216:219], v[32:35]
	v_mfma_f32_16x16x32_bf16 v[60:63], v[176:179], v[196:199], v[60:63]
	v_mfma_f32_16x16x32_bf16 v[56:59], v[188:191], v[196:199], v[56:59]
	v_mfma_f32_16x16x32_bf16 v[52:55], v[176:179], v[204:207], v[52:55]
	v_mfma_f32_16x16x32_bf16 v[48:51], v[188:191], v[204:207], v[48:51]
	v_mfma_f32_16x16x32_bf16 v[44:47], v[176:179], v[212:215], v[44:47]
	v_mfma_f32_16x16x32_bf16 v[40:43], v[188:191], v[212:215], v[40:43]
	v_mfma_f32_16x16x32_bf16 v[36:39], v[176:179], v[220:223], v[36:39]
	v_mfma_f32_16x16x32_bf16 v[32:35], v[188:191], v[220:223], v[32:35]
	s_setprio 0
	s_barrier
	v_readfirstlane_b32 s1, v157
	v_lshl_add_u64 v[172:173], v[242:243], 0, s[42:43]
	s_mov_b32 m0, s1
	v_readfirstlane_b32 s1, v158
	global_load_lds_dwordx4 v[172:173], off
	v_lshl_add_u64 v[172:173], v[244:245], 0, s[42:43]
	s_mov_b32 m0, s1
	s_nop 0
	global_load_lds_dwordx4 v[172:173], off
	s_cmp_eq_u32 s0, -2
	s_cselect_b32 s1, s98, 0
	s_cmp_lg_u32 s1, 0
	s_cbranch_scc1 .Lg4_w22
	s_waitcnt vmcnt(6)
; #define STAGE(P, BASE, br, kt) do { const long _g = (long)(br) * K + (long)(kt) * 64; \
;     _Pragma("unroll") for (int _i = 0; _i < 2; ++_i) { const int _b = tidx * 16 + _i * 8192; int _r, _c; stage_rc8(_b, _r, _c); \
;       __builtin_amdgcn_global_load_lds((const unsigned*)(BASE + _g + (long)_r * K + _c), (LAS unsigned*)((LAS char*)(P) + _b), 16, 0, 0); } } while (0)
; #define LDA(dst, b, h) _Pragma("unroll") for (int m = 0; m < 4; ++m) _Pragma("unroll") for (int k = 0; k < 2; ++k) \
;     dst[m][k] = *reinterpret_cast<const bf16x8*>((const char*)SA(b, h) + lds_byte8(wr * 64 + m * 16 + fr, k * 32 + fq * 8))
; #define LDB(dst, b, h) _Pragma("unroll") for (int n = 0; n < 2; ++n) _Pragma("unroll") for (int k = 0; k < 2; ++k) \
;     dst[n][k] = *reinterpret_cast<const bf16x8*>((const char*)SB(b, h) + lds_byte8(wc * 32 + n * 16 + fr, k * 32 + fq * 8))
; #define MMA(ai, bj, At_, Bt_) do { __builtin_amdgcn_s_setprio(1); \
;     _Pragma("unroll") for (int m = 0; m < 4; ++m) _Pragma("unroll") for (int n = 0; n < 2; ++n) _Pragma("unroll") for (int k = 0; k < 2; ++k) \
;       acc[ai][bj][m][n] = MFMA16(Bt_[n][k], At_[m][k], acc[ai][bj][m][n]); \
;     __builtin_amdgcn_s_setprio(0); } while (0)
; #define WAIT_V(n) asm volatile("s_waitcnt vmcnt(" #n ")" ::: "memory")
; #define WAIT_L(n) asm volatile("s_waitcnt lgkmcnt(" #n ")" ::: "memory")
; #define BAR __builtin_amdgcn_s_barrier()
; #define SCHED __builtin_amdgcn_sched_barrier(0)
; template <class FL, class FS>
; DI void gemm8_tile(char* shmc, const bf16_t* __restrict__ A, const bf16_t* __restrict__ Bt, const int K, const int brow, const int bcol, FL fl, FS fs) {
;     ...
;     WAIT_V(6); BAR; MMA(1, 1, At, B1); BAR;
;     LDB(B0, 1, 0); SCHED; LDA(At, 1, 0); STAGE(SA(0, 1), A, brow + HALF, t + 2);
;     WAIT_L(8); BAR; WAIT_L(0); MMA(0, 0, At, B0); BAR; SCHED;
;     LDB(B1, 1, 1); STAGE(SB(1, 0), Bt, bcol, t + 3);
;     BAR; WAIT_L(0); MMA(0, 1, At, B1); BAR;
;     LDA(At, 1, 1); STAGE(SA(1, 0), A, brow, t + 3);
;     BAR; WAIT_L(0); MMA(1, 0, At, B0); BAR; SCHED;
;     STAGE(SB(1, 1), Bt, bcol + HALF, t + 3);
;     WAIT_V(6); BAR; MMA(1, 1, At, B1); BAR;
.Lg4_wd:
	s_barrier
	s_setprio 1
	v_mfma_f32_16x16x32_bf16 v[28:31], v[224:227], v[192:195], v[28:31]
	v_mfma_f32_16x16x32_bf16 v[24:27], v[232:235], v[192:195], v[24:27]
	v_mfma_f32_16x16x32_bf16 v[20:23], v[224:227], v[200:203], v[20:23]
	v_mfma_f32_16x16x32_bf16 v[16:19], v[232:235], v[200:203], v[16:19]
	v_mfma_f32_16x16x32_bf16 v[12:15], v[224:227], v[208:211], v[12:15]
	v_mfma_f32_16x16x32_bf16 v[8:11], v[232:235], v[208:211], v[8:11]
	v_mfma_f32_16x16x32_bf16 v[4:7], v[224:227], v[216:219], v[4:7]
	v_mfma_f32_16x16x32_bf16 v[0:3], v[232:235], v[216:219], v[0:3]
	v_mfma_f32_16x16x32_bf16 v[28:31], v[228:231], v[196:199], v[28:31]
	v_mfma_f32_16x16x32_bf16 v[24:27], v[236:239], v[196:199], v[24:27]
	v_mfma_f32_16x16x32_bf16 v[20:23], v[228:231], v[204:207], v[20:23]
	v_mfma_f32_16x16x32_bf16 v[16:19], v[236:239], v[204:207], v[16:19]
	v_mfma_f32_16x16x32_bf16 v[12:15], v[228:231], v[212:215], v[12:15]
	v_mfma_f32_16x16x32_bf16 v[8:11], v[236:239], v[212:215], v[8:11]
	v_mfma_f32_16x16x32_bf16 v[4:7], v[228:231], v[220:223], v[4:7]
	v_mfma_f32_16x16x32_bf16 v[0:3], v[236:239], v[220:223], v[0:3]
	s_setprio 0
	s_barrier
	ds_read_b128 v[172:175], v156
	ds_read_b128 v[176:179], v156 offset:1024
	ds_read_b128 v[184:187], v156 offset:2048
	ds_read_b128 v[188:191], v156 offset:3072
	v_readfirstlane_b32 s1, v159
	v_lshl_add_u64 v[224:225], v[180:181], 0, s[44:45]
	s_mov_b32 m0, s1
	v_readfirstlane_b32 s1, v160
	ds_read_b128 v[192:195], v152 offset:32768
	ds_read_b128 v[196:199], v152 offset:33792
	ds_read_b128 v[200:203], v151 offset:32768
	ds_read_b128 v[204:207], v151 offset:33792
	ds_read_b128 v[208:211], v150 offset:32768
	ds_read_b128 v[212:215], v150 offset:33792
	ds_read_b128 v[216:219], v148 offset:32768
	ds_read_b128 v[220:223], v148 offset:33792
	global_load_lds_dwordx4 v[224:225], off
	v_lshl_add_u64 v[224:225], v[240:241], 0, s[44:45]
	s_mov_b32 m0, s1
	s_nop 0
	global_load_lds_dwordx4 v[224:225], off
	s_waitcnt lgkmcnt(8)
	s_barrier
	s_waitcnt lgkmcnt(0)
	s_setprio 1
	s_waitcnt lgkmcnt(0)
	v_mfma_f32_16x16x32_bf16 v[124:127], v[172:175], v[192:195], v[124:127]
	v_mfma_f32_16x16x32_bf16 v[120:123], v[184:187], v[192:195], v[120:123]
	v_mfma_f32_16x16x32_bf16 v[116:119], v[172:175], v[200:203], v[116:119]
	v_mfma_f32_16x16x32_bf16 v[112:115], v[184:187], v[200:203], v[112:115]
	v_mfma_f32_16x16x32_bf16 v[108:111], v[172:175], v[208:211], v[108:111]
	v_mfma_f32_16x16x32_bf16 v[104:107], v[184:187], v[208:211], v[104:107]
	v_mfma_f32_16x16x32_bf16 v[100:103], v[172:175], v[216:219], v[100:103]
	v_mfma_f32_16x16x32_bf16 v[96:99], v[184:187], v[216:219], v[96:99]
	v_mfma_f32_16x16x32_bf16 v[124:127], v[176:179], v[196:199], v[124:127]
	v_mfma_f32_16x16x32_bf16 v[120:123], v[188:191], v[196:199], v[120:123]
	v_mfma_f32_16x16x32_bf16 v[116:119], v[176:179], v[204:207], v[116:119]
	v_mfma_f32_16x16x32_bf16 v[112:115], v[188:191], v[204:207], v[112:115]
	v_mfma_f32_16x16x32_bf16 v[108:111], v[176:179], v[212:215], v[108:111]
	v_mfma_f32_16x16x32_bf16 v[104:107], v[188:191], v[212:215], v[104:107]
	v_mfma_f32_16x16x32_bf16 v[100:103], v[176:179], v[220:223], v[100:103]
	v_mfma_f32_16x16x32_bf16 v[96:99], v[188:191], v[220:223], v[96:99]
	s_setprio 0
	s_barrier
	v_readfirstlane_b32 s1, v161
	v_lshl_add_u64 v[246:247], v[242:243], 0, s[46:47]
	s_mov_b32 m0, s1
	v_readfirstlane_b32 s1, v162
	ds_read_b128 v[224:227], v154
	ds_read_b128 v[228:231], v154 offset:1024
	ds_read_b128 v[232:235], v154 offset:2048
	ds_read_b128 v[236:239], v154 offset:3072
	global_load_lds_dwordx4 v[246:247], off
	v_lshl_add_u64 v[246:247], v[244:245], 0, s[46:47]
	s_mov_b32 m0, s1
	s_nop 0
	global_load_lds_dwordx4 v[246:247], off
	s_barrier
	s_waitcnt lgkmcnt(0)
	s_setprio 1
	s_waitcnt lgkmcnt(0)
	v_mfma_f32_16x16x32_bf16 v[92:95], v[224:227], v[192:195], v[92:95]
	v_mfma_f32_16x16x32_bf16 v[88:91], v[232:235], v[192:195], v[88:91]
	v_mfma_f32_16x16x32_bf16 v[84:87], v[224:227], v[200:203], v[84:87]
	v_mfma_f32_16x16x32_bf16 v[80:83], v[232:235], v[200:203], v[80:83]
	v_mfma_f32_16x16x32_bf16 v[76:79], v[224:227], v[208:211], v[76:79]
	v_mfma_f32_16x16x32_bf16 v[72:75], v[232:235], v[208:211], v[72:75]
	v_mfma_f32_16x16x32_bf16 v[68:71], v[224:227], v[216:219], v[68:71]
	v_mfma_f32_16x16x32_bf16 v[64:67], v[232:235], v[216:219], v[64:67]
	v_mfma_f32_16x16x32_bf16 v[92:95], v[228:231], v[196:199], v[92:95]
	v_mfma_f32_16x16x32_bf16 v[88:91], v[236:239], v[196:199], v[88:91]
	v_mfma_f32_16x16x32_bf16 v[84:87], v[228:231], v[204:207], v[84:87]
	v_mfma_f32_16x16x32_bf16 v[80:83], v[236:239], v[204:207], v[80:83]
	v_mfma_f32_16x16x32_bf16 v[76:79], v[228:231], v[212:215], v[76:79]
	v_mfma_f32_16x16x32_bf16 v[72:75], v[236:239], v[212:215], v[72:75]
	v_mfma_f32_16x16x32_bf16 v[68:71], v[228:231], v[220:223], v[68:71]
	v_mfma_f32_16x16x32_bf16 v[64:67], v[236:239], v[220:223], v[64:67]
	s_setprio 0
	v_readfirstlane_b32 s1, v163
	v_lshl_add_u64 v[180:181], v[180:181], 0, s[48:49]
	s_mov_b32 m0, s1
	v_readfirstlane_b32 s1, v164
	s_barrier
	ds_read_b128 v[192:195], v152 offset:49152
	ds_read_b128 v[196:199], v152 offset:50176
	ds_read_b128 v[200:203], v151 offset:49152
	ds_read_b128 v[204:207], v151 offset:50176
	ds_read_b128 v[208:211], v150 offset:49152
	ds_read_b128 v[212:215], v150 offset:50176
	ds_read_b128 v[216:219], v148 offset:49152
	ds_read_b128 v[220:223], v148 offset:50176
	global_load_lds_dwordx4 v[180:181], off
	v_lshl_add_u64 v[180:181], v[240:241], 0, s[48:49]
	s_mov_b32 m0, s1
	s_nop 0
	global_load_lds_dwordx4 v[180:181], off
	s_barrier
; #define STAGE(P, BASE, br, kt) do { const long _g = (long)(br) * K + (long)(kt) * 64; \
;     _Pragma("unroll") for (int _i = 0; _i < 2; ++_i) { const int _b = tidx * 16 + _i * 8192; int _r, _c; stage_rc8(_b, _r, _c); \
;       __builtin_amdgcn_global_load_lds((const unsigned*)(BASE + _g + (long)_r * K + _c), (LAS unsigned*)((LAS char*)(P) + _b), 16, 0, 0); } } while (0)
; #define LDA(dst, b, h) _Pragma("unroll") for (int m = 0; m < 4; ++m) _Pragma("unroll") for (int k = 0; k < 2; ++k) \
;     dst[m][k] = *reinterpret_cast<const bf16x8*>((const char*)SA(b, h) + lds_byte8(wr * 64 + m * 16 + fr, k * 32 + fq * 8))
; #define LDB(dst, b, h) _Pragma("unroll") for (int n = 0; n < 2; ++n) _Pragma("unroll") for (int k = 0; k < 2; ++k) \
;     dst[n][k] = *reinterpret_cast<const bf16x8*>((const char*)SB(b, h) + lds_byte8(wc * 32 + n * 16 + fr, k * 32 + fq * 8))
; #define MMA(ai, bj, At_, Bt_) do { __builtin_amdgcn_s_setprio(1); \
;     _Pragma("unroll") for (int m = 0; m < 4; ++m) _Pragma("unroll") for (int n = 0; n < 2; ++n) _Pragma("unroll") for (int k = 0; k < 2; ++k) \
;       acc[ai][bj][m][n] = MFMA16(Bt_[n][k], At_[m][k], acc[ai][bj][m][n]); \
;     __builtin_amdgcn_s_setprio(0); } while (0)
; #define WAIT_V(n) asm volatile("s_waitcnt vmcnt(" #n ")" ::: "memory")
; #define WAIT_L(n) asm volatile("s_waitcnt lgkmcnt(" #n ")" ::: "memory")
; #define BAR __builtin_amdgcn_s_barrier()
; #define SCHED __builtin_amdgcn_sched_barrier(0)
; template <class FL, class FS>
; DI void gemm8_tile(char* shmc, const bf16_t* __restrict__ A, const bf16_t* __restrict__ Bt, const int K, const int brow, const int bcol, FL fl, FS fs) {
;     ...
;     BAR; WAIT_L(0); MMA(1, 0, At, B0); BAR; SCHED;
;     STAGE(SB(1, 1), Bt, bcol + HALF, t + 3);
;     WAIT_V(6); BAR; MMA(1, 1, At, B1); BAR;
;   }
;   { LDB(B0, 0, 0); LDA(At, 0, 0); STAGE(SA(1, 1), A, brow + HALF, nt - 1);
;     BAR; WAIT_L(0); MMA(0, 0, At, B0); BAR;
;     LDB(B1, 0, 1); BAR; WAIT_L(0); MMA(0, 1, At, B1); BAR;
;     LDA(At, 0, 1); WAIT_V(4); BAR; WAIT_L(0); MMA(1, 0, At, B0); MMA(1, 1, At, B1); BAR; }
	s_waitcnt lgkmcnt(0)
	s_setprio 1
	s_waitcnt lgkmcnt(0)
	v_mfma_f32_16x16x32_bf16 v[60:63], v[172:175], v[192:195], v[60:63]
	v_mfma_f32_16x16x32_bf16 v[56:59], v[184:187], v[192:195], v[56:59]
	v_mfma_f32_16x16x32_bf16 v[52:55], v[172:175], v[200:203], v[52:55]
	v_mfma_f32_16x16x32_bf16 v[48:51], v[184:187], v[200:203], v[48:51]
	v_mfma_f32_16x16x32_bf16 v[44:47], v[172:175], v[208:211], v[44:47]
	v_mfma_f32_16x16x32_bf16 v[40:43], v[184:187], v[208:211], v[40:43]
	v_mfma_f32_16x16x32_bf16 v[36:39], v[172:175], v[216:219], v[36:39]
	v_mfma_f32_16x16x32_bf16 v[32:35], v[184:187], v[216:219], v[32:35]
	v_mfma_f32_16x16x32_bf16 v[60:63], v[176:179], v[196:199], v[60:63]
	v_mfma_f32_16x16x32_bf16 v[56:59], v[188:191], v[196:199], v[56:59]
	v_mfma_f32_16x16x32_bf16 v[52:55], v[176:179], v[204:207], v[52:55]
	v_mfma_f32_16x16x32_bf16 v[48:51], v[188:191], v[204:207], v[48:51]
	v_mfma_f32_16x16x32_bf16 v[44:47], v[176:179], v[212:215], v[44:47]
	v_mfma_f32_16x16x32_bf16 v[40:43], v[188:191], v[212:215], v[40:43]
	v_mfma_f32_16x16x32_bf16 v[36:39], v[176:179], v[220:223], v[36:39]
	v_mfma_f32_16x16x32_bf16 v[32:35], v[188:191], v[220:223], v[32:35]
	s_setprio 0
	s_barrier
	v_readfirstlane_b32 s1, v165
	v_lshl_add_u64 v[172:173], v[242:243], 0, s[50:51]
	s_mov_b32 m0, s1
	v_readfirstlane_b32 s1, v167
	global_load_lds_dwordx4 v[172:173], off
	v_lshl_add_u64 v[172:173], v[244:245], 0, s[50:51]
	s_mov_b32 m0, s1
	s_nop 0
	global_load_lds_dwordx4 v[172:173], off
	s_waitcnt vmcnt(6)
	s_barrier
	s_setprio 1
	v_mfma_f32_16x16x32_bf16 v[28:31], v[224:227], v[192:195], v[28:31]
	v_mfma_f32_16x16x32_bf16 v[24:27], v[232:235], v[192:195], v[24:27]
	v_mfma_f32_16x16x32_bf16 v[20:23], v[224:227], v[200:203], v[20:23]
	v_mfma_f32_16x16x32_bf16 v[16:19], v[232:235], v[200:203], v[16:19]
	v_mfma_f32_16x16x32_bf16 v[12:15], v[224:227], v[208:211], v[12:15]
	v_mfma_f32_16x16x32_bf16 v[8:11], v[232:235], v[208:211], v[8:11]
	v_mfma_f32_16x16x32_bf16 v[4:7], v[224:227], v[216:219], v[4:7]
	v_mfma_f32_16x16x32_bf16 v[0:3], v[232:235], v[216:219], v[0:3]
	v_mfma_f32_16x16x32_bf16 v[28:31], v[228:231], v[196:199], v[28:31]
	v_mfma_f32_16x16x32_bf16 v[24:27], v[236:239], v[196:199], v[24:27]
	v_mfma_f32_16x16x32_bf16 v[20:23], v[228:231], v[204:207], v[20:23]
	v_mfma_f32_16x16x32_bf16 v[16:19], v[236:239], v[204:207], v[16:19]
	v_mfma_f32_16x16x32_bf16 v[12:15], v[228:231], v[212:215], v[12:15]
	v_mfma_f32_16x16x32_bf16 v[8:11], v[236:239], v[212:215], v[8:11]
	v_mfma_f32_16x16x32_bf16 v[4:7], v[228:231], v[220:223], v[4:7]
	v_mfma_f32_16x16x32_bf16 v[0:3], v[236:239], v[220:223], v[0:3]
	s_setprio 0
	s_add_i32 s0, s0, 2
	v_lshl_add_u64 v[134:135], v[134:135], 0, s[52:53]
	v_lshl_add_u64 v[136:137], v[136:137], 0, s[52:53]
	v_lshl_add_u64 v[138:139], v[138:139], 0, s[52:53]
	s_cmp_lt_u32 s0, 12
	v_lshl_add_u64 v[140:141], v[140:141], 0, s[52:53]
	s_barrier
	s_cbranch_scc1 .LBB0_869
	v_readfirstlane_b32 s0, v169
	v_lshl_add_u64 v[130:131], v[130:131], 0, s[54:55]
	s_mov_b32 m0, s0
	v_readfirstlane_b32 s0, v168
	ds_read_b128 v[134:137], v170
	ds_read_b128 v[138:141], v170 offset:1024
	ds_read_b128 v[158:161], v170 offset:2048
	ds_read_b128 v[162:165], v170 offset:3072
	ds_read_b128 v[170:173], v152
	ds_read_b128 v[174:177], v152 offset:1024
	ds_read_b128 v[178:181], v151
	ds_read_b128 v[184:187], v151 offset:1024
	ds_read_b128 v[188:191], v150
	ds_read_b128 v[192:195], v150 offset:1024
	ds_read_b128 v[196:199], v148
	ds_read_b128 v[200:203], v148 offset:1024
	global_load_lds_dwordx4 v[130:131], off
	v_lshl_add_u64 v[130:131], v[132:133], 0, s[54:55]
	s_mov_b32 m0, s0
	s_nop 0
	global_load_lds_dwordx4 v[130:131], off
	s_barrier
	s_waitcnt lgkmcnt(0)
	s_setprio 1
	s_waitcnt lgkmcnt(0)
	v_mfma_f32_16x16x32_bf16 v[124:127], v[134:137], v[170:173], v[124:127]
	v_mfma_f32_16x16x32_bf16 v[120:123], v[158:161], v[170:173], v[120:123]
	v_mfma_f32_16x16x32_bf16 v[116:119], v[134:137], v[178:181], v[116:119]
	v_mfma_f32_16x16x32_bf16 v[112:115], v[158:161], v[178:181], v[112:115]
	v_mfma_f32_16x16x32_bf16 v[100:103], v[134:137], v[196:199], v[100:103]
	v_mfma_f32_16x16x32_bf16 v[96:99], v[158:161], v[196:199], v[96:99]
	v_mfma_f32_16x16x32_bf16 v[124:127], v[138:141], v[174:177], v[124:127]
	v_mfma_f32_16x16x32_bf16 v[120:123], v[162:165], v[174:177], v[120:123]
	v_mfma_f32_16x16x32_bf16 v[116:119], v[138:141], v[184:187], v[116:119]
	v_mfma_f32_16x16x32_bf16 v[112:115], v[162:165], v[184:187], v[112:115]
	v_mfma_f32_16x16x32_bf16 v[108:111], v[134:137], v[188:191], v[108:111]
	v_mfma_f32_16x16x32_bf16 v[104:107], v[158:161], v[188:191], v[104:107]
	v_mfma_f32_16x16x32_bf16 v[100:103], v[138:141], v[200:203], v[100:103]
	v_mfma_f32_16x16x32_bf16 v[96:99], v[162:165], v[200:203], v[96:99]
	v_mfma_f32_16x16x32_bf16 v[130:133], v[138:141], v[192:195], v[108:111]
	v_mfma_f32_16x16x32_bf16 v[204:207], v[162:165], v[192:195], v[104:107]
	s_setprio 0
	s_barrier
	s_nop 0
	ds_read_b128 v[104:107], v166
	ds_read_b128 v[108:111], v166 offset:1024
	ds_read_b128 v[208:211], v166 offset:2048
	ds_read_b128 v[166:169], v166 offset:3072
	s_barrier
; #define LDA(dst, b, h) _Pragma("unroll") for (int m = 0; m < 4; ++m) _Pragma("unroll") for (int k = 0; k < 2; ++k) \
;     dst[m][k] = *reinterpret_cast<const bf16x8*>((const char*)SA(b, h) + lds_byte8(wr * 64 + m * 16 + fr, k * 32 + fq * 8))
; #define LDB(dst, b, h) _Pragma("unroll") for (int n = 0; n < 2; ++n) _Pragma("unroll") for (int k = 0; k < 2; ++k) \
;     dst[n][k] = *reinterpret_cast<const bf16x8*>((const char*)SB(b, h) + lds_byte8(wc * 32 + n * 16 + fr, k * 32 + fq * 8))
; #define MMA(ai, bj, At_, Bt_) do { __builtin_amdgcn_s_setprio(1); \
;     _Pragma("unroll") for (int m = 0; m < 4; ++m) _Pragma("unroll") for (int n = 0; n < 2; ++n) _Pragma("unroll") for (int k = 0; k < 2; ++k) \
;       acc[ai][bj][m][n] = MFMA16(Bt_[n][k], At_[m][k], acc[ai][bj][m][n]); \
;     __builtin_amdgcn_s_setprio(0); } while (0)
; #define WAIT_V(n) asm volatile("s_waitcnt vmcnt(" #n ")" ::: "memory")
; #define WAIT_L(n) asm volatile("s_waitcnt lgkmcnt(" #n ")" ::: "memory")
; #define BAR __builtin_amdgcn_s_barrier()
; template <class FL, class FS>
; DI void gemm8_tile(char* shmc, const bf16_t* __restrict__ A, const bf16_t* __restrict__ Bt, const int K, const int brow, const int bcol, FL fl, FS fs) {
;     ...
;     BAR; WAIT_L(0); MMA(0, 0, At, B0); BAR;
;     LDB(B1, 0, 1); BAR; WAIT_L(0); MMA(0, 1, At, B1); BAR;
;     LDA(At, 0, 1); WAIT_V(4); BAR; WAIT_L(0); MMA(1, 0, At, B0); MMA(1, 1, At, B1); BAR; }
;   { LDB(B0, 1, 0); LDA(At, 1, 0); WAIT_V(2); BAR; WAIT_L(0); MMA(0, 0, At, B0); BAR;
;     LDB(B1, 1, 1); WAIT_V(0); BAR; WAIT_L(0); MMA(0, 1, At, B1); BAR;
;     LDA(At, 1, 1); BAR; WAIT_L(0); MMA(1, 0, At, B0); MMA(1, 1, At, B1); BAR; }
	s_waitcnt lgkmcnt(0)
	s_setprio 1
	s_waitcnt lgkmcnt(3)
	v_mfma_f32_16x16x32_bf16 v[84:87], v[104:107], v[178:181], v[84:87]
	s_waitcnt lgkmcnt(1)
	v_mfma_f32_16x16x32_bf16 v[80:83], v[208:211], v[178:181], v[80:83]
	v_mfma_f32_16x16x32_bf16 v[68:71], v[104:107], v[196:199], v[68:71]
	v_mfma_f32_16x16x32_bf16 v[64:67], v[208:211], v[196:199], v[64:67]
	v_mfma_f32_16x16x32_bf16 v[92:95], v[104:107], v[170:173], v[92:95]
	v_mfma_f32_16x16x32_bf16 v[88:91], v[208:211], v[170:173], v[88:91]
	v_mfma_f32_16x16x32_bf16 v[84:87], v[108:111], v[184:187], v[84:87]
	s_waitcnt lgkmcnt(0)
	v_mfma_f32_16x16x32_bf16 v[80:83], v[166:169], v[184:187], v[80:83]
	v_mfma_f32_16x16x32_bf16 v[76:79], v[104:107], v[188:191], v[76:79]
	v_mfma_f32_16x16x32_bf16 v[72:75], v[208:211], v[188:191], v[72:75]
	v_mfma_f32_16x16x32_bf16 v[68:71], v[108:111], v[200:203], v[68:71]
	v_mfma_f32_16x16x32_bf16 v[64:67], v[166:169], v[200:203], v[64:67]
	v_mfma_f32_16x16x32_bf16 v[212:215], v[108:111], v[174:177], v[92:95]
	v_mfma_f32_16x16x32_bf16 v[170:173], v[166:169], v[174:177], v[88:91]
	v_mfma_f32_16x16x32_bf16 v[174:177], v[108:111], v[192:195], v[76:79]
	v_mfma_f32_16x16x32_bf16 v[178:181], v[166:169], v[192:195], v[72:75]
	s_setprio 0
	s_barrier
	s_nop 0
	ds_read_b128 v[72:75], v152 offset:16384
	ds_read_b128 v[76:79], v152 offset:17408
	ds_read_b128 v[88:91], v151 offset:16384
	ds_read_b128 v[92:95], v151 offset:17408
	ds_read_b128 v[184:187], v150 offset:16384
	ds_read_b128 v[188:191], v150 offset:17408
	ds_read_b128 v[192:195], v148 offset:16384
	ds_read_b128 v[196:199], v148 offset:17408
	s_waitcnt vmcnt(4)
	s_barrier
	s_waitcnt lgkmcnt(0)
	s_setprio 1
	s_waitcnt lgkmcnt(7)
	v_mfma_f32_16x16x32_bf16 v[60:63], v[134:137], v[72:75], v[60:63]
	v_mfma_f32_16x16x32_bf16 v[56:59], v[158:161], v[72:75], v[56:59]
	s_waitcnt lgkmcnt(5)
	v_mfma_f32_16x16x32_bf16 v[52:55], v[134:137], v[88:91], v[52:55]
	v_mfma_f32_16x16x32_bf16 v[48:51], v[158:161], v[88:91], v[48:51]
	s_waitcnt lgkmcnt(1)
	v_mfma_f32_16x16x32_bf16 v[36:39], v[134:137], v[192:195], v[36:39]
	v_mfma_f32_16x16x32_bf16 v[32:35], v[158:161], v[192:195], v[32:35]
	v_mfma_f32_16x16x32_bf16 v[60:63], v[138:141], v[76:79], v[60:63]
	v_mfma_f32_16x16x32_bf16 v[56:59], v[162:165], v[76:79], v[56:59]
	v_mfma_f32_16x16x32_bf16 v[52:55], v[138:141], v[92:95], v[52:55]
	v_mfma_f32_16x16x32_bf16 v[48:51], v[162:165], v[92:95], v[48:51]
	v_mfma_f32_16x16x32_bf16 v[44:47], v[134:137], v[184:187], v[44:47]
	v_mfma_f32_16x16x32_bf16 v[40:43], v[158:161], v[184:187], v[40:43]
	s_waitcnt lgkmcnt(0)
	v_mfma_f32_16x16x32_bf16 v[36:39], v[138:141], v[196:199], v[36:39]
	v_mfma_f32_16x16x32_bf16 v[32:35], v[162:165], v[196:199], v[32:35]
	v_mfma_f32_16x16x32_bf16 v[200:203], v[138:141], v[188:191], v[44:47]
	v_mfma_f32_16x16x32_bf16 v[216:219], v[162:165], v[188:191], v[40:43]
	s_setprio 0
	s_setprio 1
	v_mfma_f32_16x16x32_bf16 v[20:23], v[104:107], v[88:91], v[20:23]
	v_mfma_f32_16x16x32_bf16 v[16:19], v[208:211], v[88:91], v[16:19]
	v_mfma_f32_16x16x32_bf16 v[4:7], v[104:107], v[192:195], v[4:7]
	v_mfma_f32_16x16x32_bf16 v[0:3], v[208:211], v[192:195], v[0:3]
	v_mfma_f32_16x16x32_bf16 v[28:31], v[104:107], v[72:75], v[28:31]
	v_mfma_f32_16x16x32_bf16 v[24:27], v[208:211], v[72:75], v[24:27]
	v_mfma_f32_16x16x32_bf16 v[20:23], v[108:111], v[92:95], v[20:23]
	v_mfma_f32_16x16x32_bf16 v[16:19], v[166:169], v[92:95], v[16:19]
	v_mfma_f32_16x16x32_bf16 v[12:15], v[104:107], v[184:187], v[12:15]
	v_mfma_f32_16x16x32_bf16 v[8:11], v[208:211], v[184:187], v[8:11]
	v_mfma_f32_16x16x32_bf16 v[4:7], v[108:111], v[196:199], v[4:7]
	v_mfma_f32_16x16x32_bf16 v[0:3], v[166:169], v[196:199], v[0:3]
	v_mfma_f32_16x16x32_bf16 v[134:137], v[108:111], v[76:79], v[28:31]
	v_mfma_f32_16x16x32_bf16 v[138:141], v[166:169], v[76:79], v[24:27]
	v_mfma_f32_16x16x32_bf16 v[158:161], v[108:111], v[188:191], v[12:15]
	v_mfma_f32_16x16x32_bf16 v[162:165], v[166:169], v[188:191], v[8:11]
	s_setprio 0
	s_barrier
	s_nop 0
	ds_read_b128 v[8:11], v156
	ds_read_b128 v[12:15], v156 offset:1024
	ds_read_b128 v[166:169], v156 offset:2048
	ds_read_b128 v[184:187], v156 offset:3072
	ds_read_b128 v[24:27], v152 offset:32768
	ds_read_b128 v[28:31], v152 offset:33792
	ds_read_b128 v[40:43], v151 offset:32768
	ds_read_b128 v[44:47], v151 offset:33792
	ds_read_b128 v[188:191], v150 offset:32768
	ds_read_b128 v[192:195], v150 offset:33792
	ds_read_b128 v[196:199], v148 offset:32768
	ds_read_b128 v[208:211], v148 offset:33792
	s_waitcnt vmcnt(2)
	s_barrier
	s_waitcnt lgkmcnt(0)
	s_setprio 1
	s_waitcnt lgkmcnt(7)
	v_mfma_f32_16x16x32_bf16 v[72:75], v[8:11], v[24:27], v[124:127]
	s_waitcnt lgkmcnt(6)
	v_mfma_f32_16x16x32_bf16 v[124:127], v[12:15], v[28:31], v[72:75]
	v_mfma_f32_16x16x32_bf16 v[72:75], v[166:169], v[24:27], v[120:123]
	v_mfma_f32_16x16x32_bf16 v[120:123], v[184:187], v[28:31], v[72:75]
	s_waitcnt lgkmcnt(5)
	v_mfma_f32_16x16x32_bf16 v[72:75], v[8:11], v[40:43], v[116:119]
	s_waitcnt lgkmcnt(4)
	v_mfma_f32_16x16x32_bf16 v[108:111], v[12:15], v[44:47], v[72:75]
	v_mfma_f32_16x16x32_bf16 v[72:75], v[166:169], v[40:43], v[112:115]
	v_mfma_f32_16x16x32_bf16 v[104:107], v[184:187], v[44:47], v[72:75]
	s_waitcnt lgkmcnt(3)
	v_mfma_f32_16x16x32_bf16 v[72:75], v[8:11], v[188:191], v[130:133]
	s_waitcnt lgkmcnt(2)
	v_mfma_f32_16x16x32_bf16 v[92:95], v[12:15], v[192:195], v[72:75]
	v_mfma_f32_16x16x32_bf16 v[72:75], v[166:169], v[188:191], v[204:207]
	v_mfma_f32_16x16x32_bf16 v[88:91], v[184:187], v[192:195], v[72:75]
	s_waitcnt lgkmcnt(1)
	v_mfma_f32_16x16x32_bf16 v[72:75], v[8:11], v[196:199], v[100:103]
	s_waitcnt lgkmcnt(0)
	v_mfma_f32_16x16x32_bf16 v[76:79], v[12:15], v[208:211], v[72:75]
	v_mfma_f32_16x16x32_bf16 v[72:75], v[166:169], v[196:199], v[96:99]
	v_mfma_f32_16x16x32_bf16 v[72:75], v[184:187], v[208:211], v[72:75]
	s_setprio 0
	s_barrier
; #define LDA(dst, b, h) _Pragma("unroll") for (int m = 0; m < 4; ++m) _Pragma("unroll") for (int k = 0; k < 2; ++k) \
;     dst[m][k] = *reinterpret_cast<const bf16x8*>((const char*)SA(b, h) + lds_byte8(wr * 64 + m * 16 + fr, k * 32 + fq * 8))
; #define LDB(dst, b, h) _Pragma("unroll") for (int n = 0; n < 2; ++n) _Pragma("unroll") for (int k = 0; k < 2; ++k) \
;     dst[n][k] = *reinterpret_cast<const bf16x8*>((const char*)SB(b, h) + lds_byte8(wc * 32 + n * 16 + fr, k * 32 + fq * 8))
; #define BAR __builtin_amdgcn_s_barrier()
; template <class FL, class FS>
; DI void gemm8_tile(char* shmc, const bf16_t* __restrict__ A, const bf16_t* __restrict__ Bt, const int K, const int brow, const int bcol, FL fl, FS fs) {
;     ...
;   { LDB(B0, 1, 0); LDA(At, 1, 0); WAIT_V(2); BAR; WAIT_L(0); MMA(0, 0, At, B0); BAR;
;     LDB(B1, 1, 1); WAIT_V(0); BAR; WAIT_L(0); MMA(0, 1, At, B1); BAR;
;     LDA(At, 1, 1); BAR; WAIT_L(0); MMA(1, 0, At, B0); MMA(1, 1, At, B1); BAR; }
;   if (wr == 0) BAR;
; #pragma unroll
;   for (int ai = 0; ai < 2; ++ai)
; #pragma unroll
;     for (int mh = 0; mh < 2; ++mh) {
;       decltype(fl(0, 0)) ld[2][2][2];
; #pragma unroll
;       for (int mm = 0; mm < 2; ++mm)
; #pragma unroll
;         for (int bj = 0; bj < 2; ++bj)
; #pragma unroll
;           for (int n = 0; n < 2; ++n) ld[mm][bj][n] = fl(brow + ai * HALF + wr * 64 + (2 * mh + mm) * 16 + fr, bcol + bj * HALF + wc * 32 + n * 16 + 4 * fq);
; #pragma unroll
;       for (int mm = 0; mm < 2; ++mm)
; #pragma unroll
;         for (int bj = 0; bj < 2; ++bj)
; #pragma unroll
;           for (int n = 0; n < 2; ++n) fs(brow + ai * HALF + wr * 64 + (2 * mh + mm) * 16 + fr, bcol + bj * HALF + wc * 32 + n * 16 + 4 * fq, acc[ai][bj][2 * mh + mm][n], ld[mm][bj][n]);
; DI void phase_g4(const Params& p, const Sub& s, char* lds_all) {
;     ...
;       [&](int row, int col, f32x4 v, const NoLoad&) {
;         if (col < 2048) {
;           st_bf4(qkv + (size_t)row * 2048 + col, v[0], v[1], v[2], v[3]);
;           if (row < MP) { const int l = row & 8191; if (l >= 8189) *(f32x4*)(p.out + O_CONV_P + ((size_t)(row >> 13) * 3 + (l - 8189)) * 2048 + col) = v; }
;           else { const int l = (row - MP) & 15; if (l >= 13) *(f32x4*)(p.out + O_CONV_S + ((size_t)((row - MP) >> 4) * 3 + (l - 13)) * 2048 + col) = v; }
;         } else if (col < 3072) st_bf4(z1 + (size_t)row * D + (col - 2048), v[0], v[1], v[2], v[3]);
	ds_read_b128 v[130:133], v154
	ds_read_b128 v[204:207], v154 offset:1024
	ds_read_b128 v[220:223], v154 offset:2048
	ds_read_b128 v[154:157], v154 offset:3072
	s_waitcnt vmcnt(0)
	s_barrier
	s_waitcnt lgkmcnt(0)
	s_setprio 1
	s_waitcnt lgkmcnt(3)
	v_mfma_f32_16x16x32_bf16 v[96:99], v[130:133], v[24:27], v[212:215]
	s_waitcnt lgkmcnt(1)
	v_mfma_f32_16x16x32_bf16 v[24:27], v[220:223], v[24:27], v[170:173]
	s_waitcnt lgkmcnt(0)
	v_mfma_f32_16x16x32_bf16 v[112:115], v[154:157], v[28:31], v[24:27]
	v_mfma_f32_16x16x32_bf16 v[24:27], v[130:133], v[40:43], v[84:87]
	v_mfma_f32_16x16x32_bf16 v[100:103], v[204:207], v[44:47], v[24:27]
	v_mfma_f32_16x16x32_bf16 v[24:27], v[220:223], v[40:43], v[80:83]
	v_mfma_f32_16x16x32_bf16 v[116:119], v[204:207], v[28:31], v[96:99]
	v_mfma_f32_16x16x32_bf16 v[96:99], v[154:157], v[44:47], v[24:27]
	v_mfma_f32_16x16x32_bf16 v[24:27], v[130:133], v[188:191], v[174:177]
	v_mfma_f32_16x16x32_bf16 v[84:87], v[204:207], v[192:195], v[24:27]
	v_mfma_f32_16x16x32_bf16 v[24:27], v[220:223], v[188:191], v[178:181]
	v_mfma_f32_16x16x32_bf16 v[80:83], v[154:157], v[192:195], v[24:27]
	v_mfma_f32_16x16x32_bf16 v[24:27], v[130:133], v[196:199], v[68:71]
	v_mfma_f32_16x16x32_bf16 v[68:71], v[204:207], v[208:211], v[24:27]
	v_mfma_f32_16x16x32_bf16 v[24:27], v[220:223], v[196:199], v[64:67]
	v_mfma_f32_16x16x32_bf16 v[64:67], v[154:157], v[208:211], v[24:27]
	s_setprio 0
	s_barrier
	ds_read_b128 v[170:173], v152 offset:49152
	ds_read_b128 v[174:177], v152 offset:50176
	ds_read_b128 v[178:181], v151 offset:49152
	ds_read_b128 v[188:191], v151 offset:50176
	ds_read_b128 v[192:195], v150 offset:49152
	ds_read_b128 v[150:153], v150 offset:50176
	ds_read_b128 v[196:199], v148 offset:49152
	ds_read_b128 v[208:211], v148 offset:50176
	s_barrier
	s_waitcnt lgkmcnt(0)
	s_setprio 1
	s_waitcnt lgkmcnt(7)
	v_mfma_f32_16x16x32_bf16 v[24:27], v[8:11], v[170:173], v[60:63]
	s_waitcnt lgkmcnt(6)
	v_mfma_f32_16x16x32_bf16 v[60:63], v[12:15], v[174:177], v[24:27]
	v_mfma_f32_16x16x32_bf16 v[24:27], v[166:169], v[170:173], v[56:59]
	v_mfma_f32_16x16x32_bf16 v[56:59], v[184:187], v[174:177], v[24:27]
	s_waitcnt lgkmcnt(5)
	v_mfma_f32_16x16x32_bf16 v[24:27], v[8:11], v[178:181], v[52:55]
	s_waitcnt lgkmcnt(4)
	v_mfma_f32_16x16x32_bf16 v[44:47], v[12:15], v[188:191], v[24:27]
	v_mfma_f32_16x16x32_bf16 v[24:27], v[166:169], v[178:181], v[48:51]
	v_mfma_f32_16x16x32_bf16 v[40:43], v[184:187], v[188:191], v[24:27]
	s_waitcnt lgkmcnt(3)
	v_mfma_f32_16x16x32_bf16 v[24:27], v[8:11], v[192:195], v[200:203]
	s_waitcnt lgkmcnt(1)
	v_mfma_f32_16x16x32_bf16 v[8:11], v[8:11], v[196:199], v[36:39]
	v_mfma_f32_16x16x32_bf16 v[28:31], v[12:15], v[150:153], v[24:27]
	v_mfma_f32_16x16x32_bf16 v[24:27], v[166:169], v[192:195], v[216:219]
	s_waitcnt lgkmcnt(0)
	v_mfma_f32_16x16x32_bf16 v[12:15], v[12:15], v[208:211], v[8:11]
	v_mfma_f32_16x16x32_bf16 v[8:11], v[166:169], v[196:199], v[32:35]
	v_mfma_f32_16x16x32_bf16 v[24:27], v[184:187], v[150:153], v[24:27]
	v_mfma_f32_16x16x32_bf16 v[8:11], v[184:187], v[208:211], v[8:11]
	s_setprio 0
	s_setprio 1
	v_mfma_f32_16x16x32_bf16 v[32:35], v[130:133], v[170:173], v[134:137]
	v_mfma_f32_16x16x32_bf16 v[52:55], v[204:207], v[174:177], v[32:35]
	v_mfma_f32_16x16x32_bf16 v[32:35], v[220:223], v[170:173], v[138:141]
	v_mfma_f32_16x16x32_bf16 v[16:19], v[220:223], v[178:181], v[16:19]
	v_mfma_f32_16x16x32_bf16 v[48:51], v[154:157], v[174:177], v[32:35]
	v_mfma_f32_16x16x32_bf16 v[20:23], v[130:133], v[178:181], v[20:23]
	v_mfma_f32_16x16x32_bf16 v[32:35], v[154:157], v[188:191], v[16:19]
	v_mfma_f32_16x16x32_bf16 v[16:19], v[130:133], v[192:195], v[158:161]
	v_mfma_f32_16x16x32_bf16 v[36:39], v[204:207], v[188:191], v[20:23]
	v_mfma_f32_16x16x32_bf16 v[20:23], v[204:207], v[150:153], v[16:19]
	v_mfma_f32_16x16x32_bf16 v[16:19], v[220:223], v[192:195], v[162:165]
	v_mfma_f32_16x16x32_bf16 v[4:7], v[130:133], v[196:199], v[4:7]
	v_mfma_f32_16x16x32_bf16 v[0:3], v[220:223], v[196:199], v[0:3]
	v_mfma_f32_16x16x32_bf16 v[16:19], v[154:157], v[150:153], v[16:19]
	v_mfma_f32_16x16x32_bf16 v[4:7], v[204:207], v[208:211], v[4:7]
	v_mfma_f32_16x16x32_bf16 v[0:3], v[154:157], v[208:211], v[0:3]
	s_setprio 0
	v_cmp_gt_u32_e32 vcc, s67, v128
	s_barrier
	s_and_saveexec_b64 s[0:1], vcc
	s_cbranch_execz .LBB0_872
	s_barrier
.LBB0_872:
	s_or_b64 exec, exec, s[0:1]
	s_mov_b32 s99, s6
	s_mov_b32 s100, s56
	s_mov_b32 s98, 1
	v_readlane_b32 s0, v251, 1
	s_add_i32 s73, s73, s0
	s_cmpk_lt_i32 s73, 0xc00
	s_cbranch_scc1 .LBB0_866
	s_mov_b32 s101, 1
.Lg4_epi:
	v_and_b32_e32 v226, 15, v182
	v_bfe_u32 v227, v182, 4, 2
	v_bfe_u32 v228, v182, 6, 2
	v_lshrrev_b32_e32 v229, 8, v182
	v_lshl_add_u32 v230, v229, 6, v226
	v_and_b32_e32 v231, 1, v227
	v_lshrrev_b32_e32 v232, 1, v227
	s_cmp_lt_u32 s100, 0x800
	s_cbranch_scc0 .Lg4_epi_z
	s_and_b32 s0, s99, 0x1f00
	s_cmp_eq_u32 s0, 0x1f00
	s_cbranch_scc0 .Lg4_epi_noconv
	v_cmp_lt_u32_e32 vcc, 12, v226
	v_cmp_eq_u32_e64 s[0:1], 1, v229
	s_and_b64 s[0:1], vcc, s[0:1]
	s_and_saveexec_b64 s[2:3], s[0:1]
	s_cbranch_execz .Lg4_epi_convskip
	v_subrev_u32_e32 v234, 13, v226
	v_lshlrev_b32_e32 v234, 13, v234
	v_lshl_add_u32 v234, v228, 7, v234
	v_lshl_add_u32 v234, v227, 4, v234
	s_lshr_b32 s8, s99, 13
	s_mul_i32 s8, s8, 0x6000
	s_lshl_b32 s9, s100, 2
	s_add_u32 s8, s8, s9
	s_add_u32 s8, s20, s8
	s_addc_u32 s9, s21, 0
	global_store_dwordx4 v234, v[12:15], s[8:9]
	global_store_dwordx4 v234, v[8:11], s[8:9] offset:64
	global_store_dwordx4 v234, v[4:7], s[8:9] offset:512
	global_store_dwordx4 v234, v[0:3], s[8:9] offset:576

; DI void st_bf4(bf16_t* p, float a, float b, float c, float d) { uint2 v; v.x = pack2(a, b); v.y = pack2(c, d); *(uint2*)p = v; }
; template <class FL, class FS>
; DI void gemm8_tile(char* shmc, const bf16_t* __restrict__ A, const bf16_t* __restrict__ Bt, const int K, const int brow, const int bcol, FL fl, FS fs) {
;     ...
; #pragma unroll
;   for (int ai = 0; ai < 2; ++ai)
; #pragma unroll
;     for (int mh = 0; mh < 2; ++mh) {
;       decltype(fl(0, 0)) ld[2][2][2];
; #pragma unroll
;       for (int mm = 0; mm < 2; ++mm)
; #pragma unroll
;         for (int bj = 0; bj < 2; ++bj)
; #pragma unroll
;           for (int n = 0; n < 2; ++n) ld[mm][bj][n] = fl(brow + ai * HALF + wr * 64 + (2 * mh + mm) * 16 + fr, bcol + bj * HALF + wc * 32 + n * 16 + 4 * fq);
; #pragma unroll
;       for (int mm = 0; mm < 2; ++mm)
; #pragma unroll
;         for (int bj = 0; bj < 2; ++bj)
; #pragma unroll
;           for (int n = 0; n < 2; ++n) fs(brow + ai * HALF + wr * 64 + (2 * mh + mm) * 16 + fr, bcol + bj * HALF + wc * 32 + n * 16 + 4 * fq, acc[ai][bj][2 * mh + mm][n], ld[mm][bj][n]);
; DI void phase_g4(const Params& p, const Sub& s, char* lds_all) {
;     ...
;       [&](int row, int col, f32x4 v, const NoLoad&) {
;         if (col < 2048) {
;           st_bf4(qkv + (size_t)row * 2048 + col, v[0], v[1], v[2], v[3]);
;           if (row < MP) { const int l = row & 8191; if (l >= 8189) *(f32x4*)(p.out + O_CONV_P + ((size_t)(row >> 13) * 3 + (l - 8189)) * 2048 + col) = v; }
;           else { const int l = (row - MP) & 15; if (l >= 13) *(f32x4*)(p.out + O_CONV_S + ((size_t)((row - MP) >> 4) * 3 + (l - 13)) * 2048 + col) = v; }
;         } else if (col < 3072) st_bf4(z1 + (size_t)row * D + (col - 2048), v[0], v[1], v[2], v[3]);
.Lg4_epi_noconv:
	v_lshlrev_b32_e32 v233, 12, v230
	v_lshl_add_u32 v233, v228, 6, v233
	v_lshl_add_u32 v233, v231, 5, v233
	v_lshl_add_u32 v233, v232, 4, v233
	s_lshl_b32 s0, s99, 12
	s_add_u32 s0, s26, s0
	s_addc_u32 s1, s27, 0
	s_lshl_b32 s2, s100, 1
	s_add_u32 s0, s0, s2
	s_addc_u32 s1, s1, 0
	v_cvt_pk_bf16_f32 v124, v124, v125
	v_cvt_pk_bf16_f32 v125, v126, v127
	v_cvt_pk_bf16_f32 v126, v120, v121
	v_cvt_pk_bf16_f32 v127, v122, v123
	v_cvt_pk_bf16_f32 v116, v116, v117
	v_cvt_pk_bf16_f32 v117, v118, v119
	v_cvt_pk_bf16_f32 v118, v112, v113
	v_cvt_pk_bf16_f32 v119, v114, v115
	v_permlane16_swap_b32_e32 v124, v126
	v_permlane16_swap_b32_e32 v125, v127
	global_store_dwordx4 v233, v[124:127], s[0:1]
	v_cvt_pk_bf16_f32 v108, v108, v109
	v_cvt_pk_bf16_f32 v109, v110, v111
	v_cvt_pk_bf16_f32 v110, v104, v105
	v_cvt_pk_bf16_f32 v111, v106, v107
	v_permlane16_swap_b32_e32 v116, v118
	v_permlane16_swap_b32_e32 v117, v119
	global_store_dwordx4 v233, v[116:119], s[0:1] offset:256
	v_cvt_pk_bf16_f32 v100, v100, v101
	v_cvt_pk_bf16_f32 v101, v102, v103
	v_cvt_pk_bf16_f32 v102, v96, v97
	v_cvt_pk_bf16_f32 v103, v98, v99
	s_add_u32 s0, s0, 0x10000
	s_addc_u32 s1, s1, 0
	v_permlane16_swap_b32_e32 v108, v110
	v_permlane16_swap_b32_e32 v109, v111
	global_store_dwordx4 v233, v[108:111], s[0:1]
	v_cvt_pk_bf16_f32 v92, v92, v93
	v_cvt_pk_bf16_f32 v93, v94, v95
	v_cvt_pk_bf16_f32 v94, v88, v89
	v_cvt_pk_bf16_f32 v95, v90, v91
	v_permlane16_swap_b32_e32 v100, v102
	v_permlane16_swap_b32_e32 v101, v103
	global_store_dwordx4 v233, v[100:103], s[0:1] offset:256
	v_cvt_pk_bf16_f32 v84, v84, v85
	v_cvt_pk_bf16_f32 v85, v86, v87
	v_cvt_pk_bf16_f32 v86, v80, v81
	v_cvt_pk_bf16_f32 v87, v82, v83
	s_add_u32 s0, s0, 0x10000
	s_addc_u32 s1, s1, 0
	v_permlane16_swap_b32_e32 v92, v94
	v_permlane16_swap_b32_e32 v93, v95
	global_store_dwordx4 v233, v[92:95], s[0:1]
	v_cvt_pk_bf16_f32 v76, v76, v77
	v_cvt_pk_bf16_f32 v77, v78, v79
	v_cvt_pk_bf16_f32 v78, v72, v73
	v_cvt_pk_bf16_f32 v79, v74, v75
	v_permlane16_swap_b32_e32 v84, v86
	v_permlane16_swap_b32_e32 v85, v87
	global_store_dwordx4 v233, v[84:87], s[0:1] offset:256
	v_cvt_pk_bf16_f32 v68, v68, v69
	v_cvt_pk_bf16_f32 v69, v70, v71
	v_cvt_pk_bf16_f32 v70, v64, v65
	v_cvt_pk_bf16_f32 v71, v66, v67
	s_add_u32 s0, s0, 0x10000
	s_addc_u32 s1, s1, 0
	v_permlane16_swap_b32_e32 v76, v78
	v_permlane16_swap_b32_e32 v77, v79
	global_store_dwordx4 v233, v[76:79], s[0:1]
	v_cvt_pk_bf16_f32 v60, v60, v61
	v_cvt_pk_bf16_f32 v61, v62, v63
	v_cvt_pk_bf16_f32 v62, v56, v57
	v_cvt_pk_bf16_f32 v63, v58, v59
	v_permlane16_swap_b32_e32 v68, v70
	v_permlane16_swap_b32_e32 v69, v71
	global_store_dwordx4 v233, v[68:71], s[0:1] offset:256
	v_cvt_pk_bf16_f32 v52, v52, v53
	v_cvt_pk_bf16_f32 v53, v54, v55
	v_cvt_pk_bf16_f32 v54, v48, v49
	v_cvt_pk_bf16_f32 v55, v50, v51
	s_add_u32 s0, s0, 0x50000
	s_addc_u32 s1, s1, 0
	v_permlane16_swap_b32_e32 v60, v62
	v_permlane16_swap_b32_e32 v61, v63
	global_store_dwordx4 v233, v[60:63], s[0:1]
	v_cvt_pk_bf16_f32 v44, v44, v45
	v_cvt_pk_bf16_f32 v45, v46, v47
	v_cvt_pk_bf16_f32 v46, v40, v41
	v_cvt_pk_bf16_f32 v47, v42, v43
	v_permlane16_swap_b32_e32 v52, v54
	v_permlane16_swap_b32_e32 v53, v55
	global_store_dwordx4 v233, v[52:55], s[0:1] offset:256
	v_cvt_pk_bf16_f32 v36, v36, v37
	v_cvt_pk_bf16_f32 v37, v38, v39
	v_cvt_pk_bf16_f32 v38, v32, v33
	v_cvt_pk_bf16_f32 v39, v34, v35
	s_add_u32 s0, s0, 0x10000
	s_addc_u32 s1, s1, 0
	v_permlane16_swap_b32_e32 v44, v46
	v_permlane16_swap_b32_e32 v45, v47
	global_store_dwordx4 v233, v[44:47], s[0:1]
	v_cvt_pk_bf16_f32 v28, v28, v29
	v_cvt_pk_bf16_f32 v29, v30, v31
	v_cvt_pk_bf16_f32 v30, v24, v25
	v_cvt_pk_bf16_f32 v31, v26, v27
	v_permlane16_swap_b32_e32 v36, v38
	v_permlane16_swap_b32_e32 v37, v39
	global_store_dwordx4 v233, v[36:39], s[0:1] offset:256
	v_cvt_pk_bf16_f32 v20, v20, v21
	v_cvt_pk_bf16_f32 v21, v22, v23
	v_cvt_pk_bf16_f32 v22, v16, v17
	v_cvt_pk_bf16_f32 v23, v18, v19
	s_add_u32 s0, s0, 0x10000
	s_addc_u32 s1, s1, 0
	v_permlane16_swap_b32_e32 v28, v30
	v_permlane16_swap_b32_e32 v29, v31
	global_store_dwordx4 v233, v[28:31], s[0:1]
	v_cvt_pk_bf16_f32 v12, v12, v13
	v_cvt_pk_bf16_f32 v13, v14, v15
	v_cvt_pk_bf16_f32 v14, v8, v9
	v_cvt_pk_bf16_f32 v15, v10, v11
	v_permlane16_swap_b32_e32 v20, v22
	v_permlane16_swap_b32_e32 v21, v23
	global_store_dwordx4 v233, v[20:23], s[0:1] offset:256
	v_cvt_pk_bf16_f32 v4, v4, v5
	v_cvt_pk_bf16_f32 v5, v6, v7
	v_cvt_pk_bf16_f32 v6, v0, v1
	v_cvt_pk_bf16_f32 v7, v2, v3
	s_add_u32 s0, s0, 0x10000
	s_addc_u32 s1, s1, 0
	v_permlane16_swap_b32_e32 v12, v14
	v_permlane16_swap_b32_e32 v13, v15
	global_store_dwordx4 v233, v[12:15], s[0:1]
	v_permlane16_swap_b32_e32 v4, v6
	v_permlane16_swap_b32_e32 v5, v7
	global_store_dwordx4 v233, v[4:7], s[0:1] offset:256
	s_branch .Lg4_epi_done
; DI void st_bf4(bf16_t* p, float a, float b, float c, float d) { uint2 v; v.x = pack2(a, b); v.y = pack2(c, d); *(uint2*)p = v; }
; template <class FL, class FS>
; DI void gemm8_tile(char* shmc, const bf16_t* __restrict__ A, const bf16_t* __restrict__ Bt, const int K, const int brow, const int bcol, FL fl, FS fs) {
;     ...
; #pragma unroll
;   for (int ai = 0; ai < 2; ++ai)
; #pragma unroll
;     for (int mh = 0; mh < 2; ++mh) {
;       decltype(fl(0, 0)) ld[2][2][2];
; #pragma unroll
;       for (int mm = 0; mm < 2; ++mm)
; #pragma unroll
;         for (int bj = 0; bj < 2; ++bj)
; #pragma unroll
;           for (int n = 0; n < 2; ++n) ld[mm][bj][n] = fl(brow + ai * HALF + wr * 64 + (2 * mh + mm) * 16 + fr, bcol + bj * HALF + wc * 32 + n * 16 + 4 * fq);
; #pragma unroll
;       for (int mm = 0; mm < 2; ++mm)
; #pragma unroll
;         for (int bj = 0; bj < 2; ++bj)
; #pragma unroll
;           for (int n = 0; n < 2; ++n) fs(brow + ai * HALF + wr * 64 + (2 * mh + mm) * 16 + fr, bcol + bj * HALF + wc * 32 + n * 16 + 4 * fq, acc[ai][bj][2 * mh + mm][n], ld[mm][bj][n]);
; DI void phase_g4(const Params& p, const Sub& s, char* lds_all) {
;     ...
;         } else if (col < 3072) st_bf4(z1 + (size_t)row * D + (col - 2048), v[0], v[1], v[2], v[3]);
.Lg4_epi_z:
	v_lshlrev_b32_e32 v233, 11, v230
	v_lshl_add_u32 v233, v228, 6, v233
	v_lshl_add_u32 v233, v231, 5, v233
	v_lshl_add_u32 v233, v232, 4, v233
	s_lshl_b32 s0, s99, 11
	s_add_u32 s0, s28, s0
	s_addc_u32 s1, s29, 0
	s_sub_u32 s2, s100, 0x800
	s_lshl_b32 s2, s2, 1
	s_add_u32 s0, s0, s2
	s_addc_u32 s1, s1, 0
	v_cvt_pk_bf16_f32 v124, v124, v125
	v_cvt_pk_bf16_f32 v125, v126, v127
	v_cvt_pk_bf16_f32 v126, v120, v121
	v_cvt_pk_bf16_f32 v127, v122, v123
	v_cvt_pk_bf16_f32 v116, v116, v117
	v_cvt_pk_bf16_f32 v117, v118, v119
	v_cvt_pk_bf16_f32 v118, v112, v113
	v_cvt_pk_bf16_f32 v119, v114, v115
	v_permlane16_swap_b32_e32 v124, v126
	v_permlane16_swap_b32_e32 v125, v127
	global_store_dwordx4 v233, v[124:127], s[0:1]
	v_cvt_pk_bf16_f32 v108, v108, v109
	v_cvt_pk_bf16_f32 v109, v110, v111
	v_cvt_pk_bf16_f32 v110, v104, v105
	v_cvt_pk_bf16_f32 v111, v106, v107
	v_permlane16_swap_b32_e32 v116, v118
	v_permlane16_swap_b32_e32 v117, v119
	global_store_dwordx4 v233, v[116:119], s[0:1] offset:256
	v_cvt_pk_bf16_f32 v100, v100, v101
	v_cvt_pk_bf16_f32 v101, v102, v103
	v_cvt_pk_bf16_f32 v102, v96, v97
	v_cvt_pk_bf16_f32 v103, v98, v99
	s_add_u32 s0, s0, 0x8000
	s_addc_u32 s1, s1, 0
	v_permlane16_swap_b32_e32 v108, v110
	v_permlane16_swap_b32_e32 v109, v111
	global_store_dwordx4 v233, v[108:111], s[0:1]
	v_cvt_pk_bf16_f32 v92, v92, v93
	v_cvt_pk_bf16_f32 v93, v94, v95
	v_cvt_pk_bf16_f32 v94, v88, v89
	v_cvt_pk_bf16_f32 v95, v90, v91
	v_permlane16_swap_b32_e32 v100, v102
	v_permlane16_swap_b32_e32 v101, v103
	global_store_dwordx4 v233, v[100:103], s[0:1] offset:256
	v_cvt_pk_bf16_f32 v84, v84, v85
	v_cvt_pk_bf16_f32 v85, v86, v87
	v_cvt_pk_bf16_f32 v86, v80, v81
	v_cvt_pk_bf16_f32 v87, v82, v83
	s_add_u32 s0, s0, 0x8000
	s_addc_u32 s1, s1, 0
	v_permlane16_swap_b32_e32 v92, v94
	v_permlane16_swap_b32_e32 v93, v95
	global_store_dwordx4 v233, v[92:95], s[0:1]
	v_cvt_pk_bf16_f32 v76, v76, v77
	v_cvt_pk_bf16_f32 v77, v78, v79
	v_cvt_pk_bf16_f32 v78, v72, v73
	v_cvt_pk_bf16_f32 v79, v74, v75
	v_permlane16_swap_b32_e32 v84, v86
	v_permlane16_swap_b32_e32 v85, v87
	global_store_dwordx4 v233, v[84:87], s[0:1] offset:256
	v_cvt_pk_bf16_f32 v68, v68, v69
	v_cvt_pk_bf16_f32 v69, v70, v71
	v_cvt_pk_bf16_f32 v70, v64, v65
	v_cvt_pk_bf16_f32 v71, v66, v67
	s_add_u32 s0, s0, 0x8000
	s_addc_u32 s1, s1, 0
	v_permlane16_swap_b32_e32 v76, v78
	v_permlane16_swap_b32_e32 v77, v79
	global_store_dwordx4 v233, v[76:79], s[0:1]
	v_cvt_pk_bf16_f32 v60, v60, v61
	v_cvt_pk_bf16_f32 v61, v62, v63
	v_cvt_pk_bf16_f32 v62, v56, v57
	v_cvt_pk_bf16_f32 v63, v58, v59
	v_permlane16_swap_b32_e32 v68, v70
	v_permlane16_swap_b32_e32 v69, v71
	global_store_dwordx4 v233, v[68:71], s[0:1] offset:256
	v_cvt_pk_bf16_f32 v52, v52, v53
	v_cvt_pk_bf16_f32 v53, v54, v55
	v_cvt_pk_bf16_f32 v54, v48, v49
	v_cvt_pk_bf16_f32 v55, v50, v51
	s_add_u32 s0, s0, 0x28000
	s_addc_u32 s1, s1, 0
	v_permlane16_swap_b32_e32 v60, v62
	v_permlane16_swap_b32_e32 v61, v63
	global_store_dwordx4 v233, v[60:63], s[0:1]
	v_cvt_pk_bf16_f32 v44, v44, v45
	v_cvt_pk_bf16_f32 v45, v46, v47
	v_cvt_pk_bf16_f32 v46, v40, v41
	v_cvt_pk_bf16_f32 v47, v42, v43
	v_permlane16_swap_b32_e32 v52, v54
	v_permlane16_swap_b32_e32 v53, v55
	global_store_dwordx4 v233, v[52:55], s[0:1] offset:256
	v_cvt_pk_bf16_f32 v36, v36, v37
	v_cvt_pk_bf16_f32 v37, v38, v39
	v_cvt_pk_bf16_f32 v38, v32, v33
	v_cvt_pk_bf16_f32 v39, v34, v35
	s_add_u32 s0, s0, 0x8000
	s_addc_u32 s1, s1, 0
	v_permlane16_swap_b32_e32 v44, v46
	v_permlane16_swap_b32_e32 v45, v47
	global_store_dwordx4 v233, v[44:47], s[0:1]
	v_cvt_pk_bf16_f32 v28, v28, v29
	v_cvt_pk_bf16_f32 v29, v30, v31
	v_cvt_pk_bf16_f32 v30, v24, v25
	v_cvt_pk_bf16_f32 v31, v26, v27
	v_permlane16_swap_b32_e32 v36, v38
	v_permlane16_swap_b32_e32 v37, v39
	global_store_dwordx4 v233, v[36:39], s[0:1] offset:256
	v_cvt_pk_bf16_f32 v20, v20, v21
	v_cvt_pk_bf16_f32 v21, v22, v23
	v_cvt_pk_bf16_f32 v22, v16, v17
	v_cvt_pk_bf16_f32 v23, v18, v19
	s_add_u32 s0, s0, 0x8000
	s_addc_u32 s1, s1, 0
	v_permlane16_swap_b32_e32 v28, v30
	v_permlane16_swap_b32_e32 v29, v31
	global_store_dwordx4 v233, v[28:31], s[0:1]
	v_cvt_pk_bf16_f32 v12, v12, v13
	v_cvt_pk_bf16_f32 v13, v14, v15
	v_cvt_pk_bf16_f32 v14, v8, v9
	v_cvt_pk_bf16_f32 v15, v10, v11
	v_permlane16_swap_b32_e32 v20, v22
	v_permlane16_swap_b32_e32 v21, v23
	global_store_dwordx4 v233, v[20:23], s[0:1] offset:256
	v_cvt_pk_bf16_f32 v4, v4, v5
	v_cvt_pk_bf16_f32 v5, v6, v7
	v_cvt_pk_bf16_f32 v6, v0, v1
	v_cvt_pk_bf16_f32 v7, v2, v3
	s_add_u32 s0, s0, 0x8000
	s_addc_u32 s1, s1, 0
	v_permlane16_swap_b32_e32 v12, v14
	v_permlane16_swap_b32_e32 v13, v15
	global_store_dwordx4 v233, v[12:15], s[0:1]
	v_permlane16_swap_b32_e32 v4, v6
	v_permlane16_swap_b32_e32 v5, v7
	global_store_dwordx4 v233, v[4:7], s[0:1] offset:256
	s_branch .Lg4_epi_done

; #define MMA(ai, bj, At_, Bt_) do { __builtin_amdgcn_s_setprio(1); \
;     _Pragma("unroll") for (int m = 0; m < 4; ++m) _Pragma("unroll") for (int n = 0; n < 2; ++n) _Pragma("unroll") for (int k = 0; k < 2; ++k) \
;       acc[ai][bj][m][n] = MFMA16(Bt_[n][k], At_[m][k], acc[ai][bj][m][n]); \
;     __builtin_amdgcn_s_setprio(0); } while (0)
; #define WAIT_V(n) asm volatile("s_waitcnt vmcnt(" #n ")" ::: "memory")
; #define BAR __builtin_amdgcn_s_barrier()
; template <class FL, class FS>
; DI void gemm8_tile(char* shmc, const bf16_t* __restrict__ A, const bf16_t* __restrict__ Bt, const int K, const int brow, const int bcol, FL fl, FS fs) {
;     ...
;     WAIT_V(6); BAR; MMA(1, 1, At, B1); BAR;
.Lg4_w22:
	s_waitcnt vmcnt(22)
	s_branch .Lg4_wd
.LBB0_1174:
	v_readlane_b32 s73, v251, 0
